# k46: k44 + static s_setprio 1 for waves 4-7 inside the attention tile loop
# speedup vs baseline: 1.0028x; 1.0028x over previous
; #define LAS __attribute__((address_space(3)))
; __device__ __forceinline__ float lane0(float v) { return __builtin_bit_cast(float, __builtin_amdgcn_readfirstlane(__builtin_bit_cast(int, v))); }
; __device__ __forceinline__ void attn_unit(const UnitDesc& u, LAS unsigned char* shm, float qkmax, float thresh) {
;     ...
;     const float ci = -Rown * LOG2E - qkmax;
;     const float kbq0 = Rq0 * LOG2E;
;     const int qabs = u.q0 + wid * 32 + r32;
;     float l_reg = 0.f; f32x16 o[2]; o[0] = f32x16{}; o[1] = f32x16{};
;     float lA = lfb[1], lB = lfb[2], lC = lfb[3];
;     { const float lf = lfb[0]; const float inc = inc4[0]; wsf[lane] = (inc - lf) * LOG2E; carry = lane0(inc);
;       *(LAS u32x4*)kdst = kreg; *(LAS u32x4*)vdst = vreg;
;       asm volatile("" : "+v"(qr[0]), "+v"(qr[1]), "+v"(qr[2]), "+v"(qr[3]));
;       asm volatile("s_waitcnt vmcnt(0)" : "+v"(kA), "+v"(vA), "+v"(kB), "+v"(vB), "+v"(kC), "+v"(vC) :: "memory"); }
;     int slot = 0, tile = NT - 1; bool stop = false;
.Lmy_prio_skip:
	ds_write_b32 v11, v10 offset:32768
	v_readfirstlane_b32 s12, v0
	s_waitcnt vmcnt(10)
	ds_write_b128 v143, v[2:5]
	ds_write_b128 v143, v[6:9] offset:8192
	v_mov_b32_e32 v0, v1
	v_mov_b32_e32 v2, v1
	v_mov_b32_e32 v3, v1
	v_mov_b32_e32 v4, v1
	v_mov_b32_e32 v5, v1
	v_mov_b32_e32 v6, v1
	v_mov_b32_e32 v7, v1
	v_mov_b32_e32 v8, v1
	v_mov_b32_e32 v9, v1
	v_mov_b32_e32 v10, v1
	v_mov_b32_e32 v11, v1
	v_mov_b32_e32 v12, v1
	v_mov_b32_e32 v13, v1
	v_mov_b64_e32 v[48:49], v[14:15]
	v_mov_b64_e32 v[64:65], v[14:15]
	v_mov_b64_e32 v[32:33], v[14:15]
	v_add3_u32 v145, 0, v16, v17
	s_add_i32 s73, s66, s49
	v_mov_b64_e32 v[46:47], v[12:13]
	v_mov_b64_e32 v[44:45], v[10:11]
	v_mov_b64_e32 v[42:43], v[8:9]
	v_mov_b64_e32 v[40:41], v[6:7]
	v_mov_b64_e32 v[38:39], v[4:5]
	v_mov_b64_e32 v[36:37], v[2:3]
	v_mov_b64_e32 v[34:35], v[0:1]
	v_mov_b64_e32 v[62:63], v[12:13]
	v_mov_b64_e32 v[60:61], v[10:11]
	v_mov_b64_e32 v[58:59], v[8:9]
	v_mov_b64_e32 v[56:57], v[6:7]
	v_mov_b64_e32 v[54:55], v[4:5]
	v_mov_b64_e32 v[52:53], v[2:3]
	v_mov_b64_e32 v[50:51], v[0:1]
	v_mov_b64_e32 v[30:31], v[12:13]
	v_mov_b64_e32 v[28:29], v[10:11]
	v_mov_b64_e32 v[26:27], v[8:9]
	v_mov_b64_e32 v[24:25], v[6:7]
	v_mov_b64_e32 v[22:23], v[4:5]
	v_mov_b64_e32 v[20:21], v[2:3]
	v_mov_b64_e32 v[18:19], v[0:1]
	v_mov_b64_e32 v[16:17], v[14:15]
	s_sub_i32 s72, s67, s28
	s_add_i32 s73, s73, 31
	v_mov_b32_e32 v113, v112
	v_mov_b32_e32 v114, v112
	v_mov_b32_e32 v115, v112
	v_mov_b32_e32 v116, v112
	v_mov_b32_e32 v117, v112
	v_mov_b32_e32 v118, v112
	v_mov_b32_e32 v119, v112
	v_mov_b32_e32 v120, v112
	v_mov_b32_e32 v121, v112
	v_mov_b32_e32 v122, v112
	v_mov_b32_e32 v123, v112
	v_mov_b32_e32 v124, v112
	v_mov_b32_e32 v125, v112
	v_mov_b32_e32 v126, v112
	v_mov_b32_e32 v127, v112
	s_lshl_b32 s75, s67, 6
	s_mov_b32 s70, 0
	v_mov_b32_e32 v148, 0
	s_mov_b64 s[62:63], 0
	v_mov_b32_e32 v150, s12
	v_mov_b64_e32 v[14:15], v[12:13]
	v_mov_b64_e32 v[12:13], v[10:11]
	v_mov_b64_e32 v[10:11], v[8:9]
	v_mov_b64_e32 v[8:9], v[6:7]
	v_mov_b64_e32 v[6:7], v[4:5]
	v_mov_b64_e32 v[4:5], v[2:3]
	v_mov_b64_e32 v[2:3], v[0:1]
	s_waitcnt vmcnt(6)
	s_branch .LBB0_777

; __device__ __forceinline__ void attn_unit(const UnitDesc& u, LAS unsigned char* shm, float qkmax, float thresh) {
;     ...
;     asm volatile("s_waitcnt vmcnt(0)" : "+v"(kA), "+v"(vA), "+v"(kB), "+v"(vB), "+v"(kC), "+v"(vC), "+v"(lA), "+v"(lB), "+v"(lC) :: "memory");
;     if (active) {
;         u32x4 zv4[4];
; #pragma unroll
;         for (int i = 0; i < 4; ++i) zv4[i] = *(const u32x4*)(u.Zg + (size_t)(wid * 32 + i * 8 + (lane >> 3)) * 512 + (lane & 7) * 8);
;         { auto rr = __builtin_amdgcn_permlane32_swap(__float_as_uint(l_reg), __float_as_uint(l_reg), false, false); l_reg = __uint_as_float(rr[0]) + __uint_as_float(rr[1]); }
.LBB0_829:
	s_or_b64 exec, exec, s[62:63]
	s_setprio 0
	s_nop 0
	s_and_b64 vcc, exec, s[12:13]
	s_cbranch_vccnz .LBB0_719
	s_nop 7
	s_nop 7
	v_mov_b64_e32 v[34:35], v[2:3]
	v_mov_b64_e32 v[36:37], v[4:5]
	v_mov_b64_e32 v[38:39], v[6:7]
	v_mov_b64_e32 v[40:41], v[8:9]
	v_mov_b64_e32 v[42:43], v[10:11]
	v_mov_b64_e32 v[44:45], v[12:13]
	v_mov_b64_e32 v[46:47], v[14:15]
	v_mov_b64_e32 v[48:49], v[16:17]
	v_mov_b64_e32 v[50:51], v[18:19]
	v_mov_b64_e32 v[52:53], v[20:21]
	v_mov_b64_e32 v[54:55], v[22:23]
	v_mov_b64_e32 v[56:57], v[24:25]
	v_mov_b64_e32 v[58:59], v[26:27]
	v_mov_b64_e32 v[60:61], v[28:29]
	v_mov_b64_e32 v[62:63], v[30:31]
	v_mov_b64_e32 v[64:65], v[32:33]
	s_lshl_b64 s[6:7], s[44:45], 1
	s_add_u32 s8, s24, s6
	v_lshrrev_b32_e32 v20, 3, v137
	s_addc_u32 s9, s25, s7
	s_lshl_b64 s[6:7], s[46:47], 1
	v_or_b32_e32 v18, s49, v20
	s_add_u32 s8, s8, s6
	v_and_b32_e32 v0, 56, v138
	v_or_b32_e32 v6, 8, v18
	s_addc_u32 s9, s9, s7
	v_lshlrev_b32_e32 v0, 1, v0
	v_ashrrev_i32_e32 v19, 31, v18
	v_ashrrev_i32_e32 v7, 31, v6
	v_lshl_add_u64 v[2:3], s[8:9], 0, v[0:1]
	v_lshlrev_b64 v[4:5], 10, v[18:19]
	v_lshlrev_b64 v[6:7], 10, v[6:7]
	v_lshl_add_u64 v[4:5], v[2:3], 0, v[4:5]
	v_lshl_add_u64 v[6:7], v[2:3], 0, v[6:7]
	global_load_dwordx4 v[14:17], v[4:5], off
	global_load_dwordx4 v[10:13], v[6:7], off
	v_or_b32_e32 v4, 16, v18
	v_or_b32_e32 v6, 24, v18
	v_ashrrev_i32_e32 v5, 31, v4
	v_ashrrev_i32_e32 v7, 31, v6
	v_lshlrev_b64 v[4:5], 10, v[4:5]
	v_lshlrev_b64 v[6:7], 10, v[6:7]
	v_lshl_add_u64 v[4:5], v[2:3], 0, v[4:5]
	v_lshl_add_u64 v[2:3], v[2:3], 0, v[6:7]
	global_load_dwordx4 v[6:9], v[4:5], off
	s_nop 0
	global_load_dwordx4 v[2:5], v[2:3], off
	v_mov_b32_e32 v21, v148
	s_lshl_b32 s8, s49, 2
	s_nop 0
	v_permlane32_swap_b32_e32 v148, v21
	s_add_i32 s10, s8, 0
	v_cmp_gt_u32_e32 vcc, 32, v137
	s_and_saveexec_b64 s[8:9], vcc
	s_cbranch_execz .LBB0_718
	v_add_f32_e32 v21, v148, v21
	v_lshl_add_u32 v22, v135, 2, s10
	ds_write_b32 v22, v21 offset:36864
	s_branch .LBB0_718
